# QKV epilogue: second halves of the cos/sin rows loaded together with the first halves (one round trip per row group instead of two), prefetch regs v246-v253
# baseline (speedup 1.0000x reference)
; __device__ __forceinline__ u32x4 pack8(const f32x4 a, const f32x4 b) { u32x4 w; w.x = cvt_pk_bf16(a[0], a[1]); w.y = cvt_pk_bf16(a[2], a[3]); w.z = cvt_pk_bf16(b[0], b[1]); w.w = cvt_pk_bf16(b[2], b[3]); return w; }
;     __device__ __forceinline__ void operator()(const f32x4 (&acc)[2][2][4][2], const Unit& u, int wr, int wc, int fr, int fq) const {
;     ...
;             f32x4 gv[2][2], cs[2][2];
; #pragma unroll
;             for (int bj = 0; bj < 2; ++bj)
; #pragma unroll
;                 for (int n = 0; n < 2; ++n) { gv[bj][n] = *(const f32x4*)(gp + 32 * bj + 8 * fq + 4 * n); cs[bj][n] = (f32x4){0.f, 0.f, 0.f, 0.f}; }
; #pragma unroll
;             for (int ai = 0; ai < 2; ++ai)
; #pragma unroll
;                 for (int m = 0; m < 4; ++m) { if (m == 0) asm volatile("" ::: "memory"); const int row = row0 + ai * HALF + m * 16; const float rs = rstd_of(ssq, row);
;                     f32x4 v[2][2]; float ss = 0.f;
; #pragma unroll
;                     for (int bj = 0; bj < 2; ++bj)
; #pragma unroll
;                         for (int n = 0; n < 2; ++n) { v[bj][n] = acc[ai][bj][m][n] * rs; const f32x4 q = v[bj][n] * v[bj][n]; ss += (q[0] + q[1]) + (q[2] + q[3]); }
;                     ss += __shfl_xor(ss, 16); ss += __shfl_xor(ss, 32);
;                     const float rn = __builtin_amdgcn_rsqf(ss * (1.0f / 64.0f) + 1e-6f);
;                     f32x4 o[2][2];
; #pragma unroll
;                     for (int n = 0; n < 2; ++n) { const f32x4 c = *(const f32x4*)(cosT + (size_t)row * 32 + 8 * fq + 4 * n), s = *(const f32x4*)(sinT + (size_t)row * 32 + 8 * fq + 4 * n);
;                         const f32x4 y1 = v[0][n] * rn * gv[0][n], y2 = v[1][n] * rn * gv[1][n];
;                         o[0][n] = y1 * c - y2 * s; o[1][n] = y2 * c + y1 * s; }
;                     if (dok) {
; #pragma unroll
;                         for (int bj = 0; bj < 2; ++bj)
; #pragma unroll
;                             for (int n = 0; n < 2; ++n) cs[bj][n] = cs[bj][n] + o[bj][n]; }
; #pragma unroll
;                     for (int bj = 0; bj < 2; ++bj) *(u32x4*)(ob + (size_t)row * 2816 + 32 * bj) = pack8(o[bj][0] * osc, o[bj][1] * osc); }
.LBB0_415:
	s_lshl_b32 s80, s1, 6
	s_ashr_i32 s81, s80, 31
	v_lshl_add_u32 v182, s78, 8, v204
	v_lshl_add_u64 v[180:181], s[80:81], 1, v[168:169]
	s_mov_b64 s[14:15], -1
	s_andn2_b64 vcc, exec, s[10:11]
	v_ashrrev_i32_e32 v183, 31, v182
	s_cbranch_vccz .LBB0_438
	global_load_dwordx4 v[136:139], v207, s[12:13] offset:16
	global_load_dwordx4 v[144:147], v207, s[12:13]
	global_load_dwordx4 v[132:135], v207, s[12:13] offset:144
	global_load_dwordx4 v[140:143], v207, s[12:13] offset:128
	v_lshl_add_u64 v[114:115], v[182:183], 4, s[18:19]
	flat_load_dwordx4 v[148:151], v[114:115]
	s_waitcnt vmcnt(0) lgkmcnt(0)
	v_mov_b32_e32 v114, v149
	v_mov_b32_e32 v115, v150
	v_mov_b32_e32 v149, v151
	v_pk_add_f32 v[114:115], v[114:115], v[148:149]
	s_nop 0
	v_add_f32_e32 v112, v114, v115
	v_fmamk_f32 v112, v112, 0x3a800000, v231
	v_rsq_f32_e32 v112, v112
	s_nop 0
	v_pk_mul_f32 v[154:155], v[128:129], v[112:113] op_sel_hi:[1,0]
	v_pk_mul_f32 v[156:157], v[130:131], v[112:113] op_sel_hi:[1,0]
	v_pk_mul_f32 v[148:149], v[154:155], v[154:155]
	v_pk_mul_f32 v[114:115], v[156:157], v[156:157]
	v_pk_mul_f32 v[160:161], v[122:123], v[112:113] op_sel_hi:[1,0]
	v_pk_mov_b32 v[150:151], v[148:149], v[114:115] op_sel:[1,0]
	v_mov_b32_e32 v149, v115
	v_pk_add_f32 v[114:115], v[150:151], v[148:149]
	v_pk_mul_f32 v[148:149], v[126:127], v[112:113] op_sel_hi:[1,0]
	v_pk_add_f32 v[162:163], v[114:115], v[114:115] op_sel_hi:[0,1]
	v_pk_mul_f32 v[114:115], v[124:125], v[112:113] op_sel_hi:[1,0]
	v_pk_mul_f32 v[150:151], v[148:149], v[148:149]
	v_pk_mul_f32 v[152:153], v[114:115], v[114:115]
	s_nop 0
	v_pk_mov_b32 v[158:159], v[152:153], v[150:151] op_sel:[1,0]
	v_mov_b32_e32 v153, v151
	v_pk_add_f32 v[150:151], v[158:159], v[152:153]
	v_pk_mul_f32 v[158:159], v[120:121], v[112:113] op_sel_hi:[1,0]
	v_pk_add_f32 v[186:187], v[150:151], v[150:151] op_sel_hi:[0,1]
	v_pk_mul_f32 v[150:151], v[160:161], v[160:161]
	v_pk_mul_f32 v[152:153], v[158:159], v[158:159]
	v_add_f32_e32 v191, v150, v151
	v_add_f32_e32 v189, v152, v153
	v_pk_mul_f32 v[150:151], v[116:117], v[112:113] op_sel_hi:[1,0]
	v_pk_mul_f32 v[152:153], v[118:119], v[112:113] op_sel_hi:[1,0]
	v_pk_mul_f32 v[194:195], v[150:151], v[150:151]
	v_pk_mul_f32 v[192:193], v[152:153], v[152:153]
	v_mov_b32_e32 v188, v194
	v_mov_b32_e32 v190, v195
	v_mov_b32_e32 v162, v192
	v_mov_b32_e32 v186, v193
	v_pk_add_f32 v[188:189], v[188:189], v[190:191]
	v_pk_add_f32 v[162:163], v[162:163], v[186:187]
	s_nop 0
	v_pk_add_f32 v[162:163], v[188:189], v[162:163]
	s_nop 0
	v_add_f32_e32 v112, v162, v163
	v_and_b32_e32 v163, 64, v236
	v_xor_b32_e32 v162, 16, v236
	v_add_u32_e32 v208, 64, v163
	v_cmp_lt_i32_e32 vcc, v162, v208
	s_nop 1
	v_cndmask_b32_e32 v162, v236, v162, vcc
	v_lshlrev_b32_e32 v209, 2, v162
	ds_bpermute_b32 v162, v209, v112
	s_waitcnt lgkmcnt(0)
	v_add_f32_e32 v112, v112, v162
	v_xor_b32_e32 v162, 32, v236
	v_cmp_lt_i32_e32 vcc, v162, v208
	s_nop 1
	v_cndmask_b32_e32 v162, v236, v162, vcc
	v_lshlrev_b32_e32 v222, 2, v162
	ds_bpermute_b32 v162, v222, v112
	s_and_b64 vcc, exec, s[82:83]
	s_waitcnt lgkmcnt(0)
	v_add_f32_e32 v112, v112, v162
	v_lshlrev_b64 v[162:163], 7, v[182:183]
	v_lshl_add_u64 v[198:199], v[170:171], 0, v[162:163]
	v_lshl_add_u64 v[162:163], v[172:173], 0, v[162:163]
	flat_load_dwordx4 v[186:189], v[198:199]
	flat_load_dwordx4 v[194:197], v[162:163]
	flat_load_dwordx4 v[246:249], v[198:199] offset:16
	flat_load_dwordx4 v[250:253], v[162:163] offset:16
	v_fmamk_f32 v112, v112, 0x3c800000, v231
	v_rsq_f32_e32 v112, v112
	s_nop 0
	v_pk_mul_f32 v[158:159], v[158:159], v[112:113] op_sel_hi:[1,0]
	v_pk_mul_f32 v[160:161], v[160:161], v[112:113] op_sel_hi:[1,0]
	v_pk_mul_f32 v[156:157], v[156:157], v[112:113] op_sel_hi:[1,0]
	v_pk_mul_f32 v[154:155], v[154:155], v[112:113] op_sel_hi:[1,0]
	v_pk_mul_f32 v[160:161], v[142:143], v[160:161]
	v_pk_mul_f32 v[158:159], v[140:141], v[158:159]
	v_pk_mul_f32 v[154:155], v[144:145], v[154:155]
	v_pk_mul_f32 v[156:157], v[146:147], v[156:157]
	v_pk_mul_f32 v[150:151], v[150:151], v[112:113] op_sel_hi:[1,0]
	v_pk_mul_f32 v[152:153], v[152:153], v[112:113] op_sel_hi:[1,0]
	v_pk_mul_f32 v[148:149], v[148:149], v[112:113] op_sel_hi:[1,0]
	v_pk_mul_f32 v[114:115], v[114:115], v[112:113] op_sel_hi:[1,0]
	v_pk_mul_f32 v[152:153], v[134:135], v[152:153]
	v_pk_mul_f32 v[150:151], v[132:133], v[150:151]
	v_pk_mul_f32 v[114:115], v[136:137], v[114:115]
	v_pk_mul_f32 v[148:149], v[138:139], v[148:149]
	s_waitcnt vmcnt(0) lgkmcnt(0)
	v_pk_mul_f32 v[192:193], v[194:195], v[158:159]
	v_pk_mul_f32 v[190:191], v[196:197], v[160:161]
	v_pk_mul_f32 v[158:159], v[186:187], v[158:159]
	v_pk_mul_f32 v[160:161], v[188:189], v[160:161]
	v_pk_fma_f32 v[190:191], v[188:189], v[156:157], v[190:191] neg_lo:[0,0,1] neg_hi:[0,0,1]
	v_pk_fma_f32 v[192:193], v[186:187], v[154:155], v[192:193] neg_lo:[0,0,1] neg_hi:[0,0,1]
	v_pk_fma_f32 v[186:187], v[196:197], v[156:157], v[160:161]
	v_pk_fma_f32 v[188:189], v[194:195], v[154:155], v[158:159]
	v_mov_b64_e32 v[154:155], v[246:247]
	v_mov_b64_e32 v[156:157], v[248:249]
	v_mov_b64_e32 v[158:159], v[250:251]
	v_mov_b64_e32 v[160:161], v[252:253]
	s_waitcnt vmcnt(0) lgkmcnt(0)
	v_pk_mul_f32 v[162:163], v[158:159], v[150:151]
	v_pk_mul_f32 v[194:195], v[160:161], v[152:153]
	v_pk_mul_f32 v[150:151], v[154:155], v[150:151]
	v_pk_mul_f32 v[152:153], v[156:157], v[152:153]
	v_pk_fma_f32 v[198:199], v[156:157], v[148:149], v[194:195] neg_lo:[0,0,1] neg_hi:[0,0,1]
	v_pk_fma_f32 v[200:201], v[154:155], v[114:115], v[162:163] neg_lo:[0,0,1] neg_hi:[0,0,1]
	v_pk_fma_f32 v[194:195], v[160:161], v[148:149], v[152:153]
	v_pk_fma_f32 v[196:197], v[158:159], v[114:115], v[150:151]
	s_cbranch_vccz .LBB0_418
	v_pk_add_f32 v[162:163], v[190:191], 0 op_sel_hi:[1,0]
	v_pk_add_f32 v[160:161], v[192:193], 0 op_sel_hi:[1,0]
	v_pk_add_f32 v[158:159], v[198:199], 0 op_sel_hi:[1,0]
	v_pk_add_f32 v[156:157], v[200:201], 0 op_sel_hi:[1,0]
	v_pk_add_f32 v[154:155], v[186:187], 0 op_sel_hi:[1,0]
	v_pk_add_f32 v[152:153], v[188:189], 0 op_sel_hi:[1,0]
	v_pk_add_f32 v[150:151], v[194:195], 0 op_sel_hi:[1,0]
	v_pk_add_f32 v[148:149], v[196:197], 0 op_sel_hi:[1,0]
	s_branch .LBB0_419

; __device__ __forceinline__ u32x4 pack8(const f32x4 a, const f32x4 b) { u32x4 w; w.x = cvt_pk_bf16(a[0], a[1]); w.y = cvt_pk_bf16(a[2], a[3]); w.z = cvt_pk_bf16(b[0], b[1]); w.w = cvt_pk_bf16(b[2], b[3]); return w; }
;     __device__ __forceinline__ void operator()(const f32x4 (&acc)[2][2][4][2], const Unit& u, int wr, int wc, int fr, int fq) const {
;     ...
;                 for (int m = 0; m < 4; ++m) { if (m == 0) asm volatile("" ::: "memory"); const int row = row0 + ai * HALF + m * 16; const float rs = rstd_of(ssq, row);
;                     f32x4 v[2][2]; float ss = 0.f;
; #pragma unroll
;                     for (int bj = 0; bj < 2; ++bj)
; #pragma unroll
;                         for (int n = 0; n < 2; ++n) { v[bj][n] = acc[ai][bj][m][n] * rs; const f32x4 q = v[bj][n] * v[bj][n]; ss += (q[0] + q[1]) + (q[2] + q[3]); }
;                     ss += __shfl_xor(ss, 16); ss += __shfl_xor(ss, 32);
;                     const float rn = __builtin_amdgcn_rsqf(ss * (1.0f / 64.0f) + 1e-6f);
;                     f32x4 o[2][2];
; #pragma unroll
;                     for (int n = 0; n < 2; ++n) { const f32x4 c = *(const f32x4*)(cosT + (size_t)row * 32 + 8 * fq + 4 * n), s = *(const f32x4*)(sinT + (size_t)row * 32 + 8 * fq + 4 * n);
;                         const f32x4 y1 = v[0][n] * rn * gv[0][n], y2 = v[1][n] * rn * gv[1][n];
;                         o[0][n] = y1 * c - y2 * s; o[1][n] = y2 * c + y1 * s; }
;                     if (dok) {
; #pragma unroll
;                         for (int bj = 0; bj < 2; ++bj)
; #pragma unroll
;                             for (int n = 0; n < 2; ++n) cs[bj][n] = cs[bj][n] + o[bj][n]; }
; #pragma unroll
;                     for (int bj = 0; bj < 2; ++bj) *(u32x4*)(ob + (size_t)row * 2816 + 32 * bj) = pack8(o[bj][0] * osc, o[bj][1] * osc); }
.LBB0_419:
	v_pk_mul_f32 v[202:203], v[184:185], v[190:191] op_sel_hi:[0,1]
	v_pk_mul_f32 v[190:191], v[184:185], v[192:193] op_sel_hi:[0,1]
	v_pk_mul_f32 v[198:199], v[184:185], v[198:199] op_sel_hi:[0,1]
	v_pk_mul_f32 v[192:193], v[184:185], v[200:201] op_sel_hi:[0,1]
	v_mad_i64_i32 v[114:115], s[10:11], v182, s92, v[180:181]
	v_cvt_pk_bf16_f32 v190, v190, v191
	v_cvt_pk_bf16_f32 v191, v202, v203
	v_cvt_pk_bf16_f32 v192, v192, v193
	v_cvt_pk_bf16_f32 v193, v198, v199
	flat_store_dwordx4 v[114:115], v[190:193]
	s_andn2_b64 vcc, exec, s[82:83]
	s_nop 0
	v_pk_mul_f32 v[190:191], v[184:185], v[186:187] op_sel_hi:[0,1]
	v_pk_mul_f32 v[186:187], v[184:185], v[188:189] op_sel_hi:[0,1]
	v_pk_mul_f32 v[192:193], v[184:185], v[194:195] op_sel_hi:[0,1]
	v_pk_mul_f32 v[188:189], v[184:185], v[196:197] op_sel_hi:[0,1]
	v_cvt_pk_bf16_f32 v186, v186, v187
	v_cvt_pk_bf16_f32 v187, v190, v191
	v_cvt_pk_bf16_f32 v188, v188, v189
	v_cvt_pk_bf16_f32 v189, v192, v193
	flat_store_dwordx4 v[114:115], v[186:189] offset:64
	v_or_b32_e32 v114, 16, v182
	v_ashrrev_i32_e32 v115, 31, v114
	v_lshl_add_u64 v[186:187], v[114:115], 4, s[18:19]
	flat_load_dwordx4 v[186:189], v[186:187]
	s_waitcnt vmcnt(0) lgkmcnt(0)
	v_mov_b32_e32 v190, v187
	v_mov_b32_e32 v191, v188
	v_mov_b32_e32 v187, v189
	v_pk_add_f32 v[186:187], v[190:191], v[186:187]
	s_nop 0
	v_add_f32_e32 v112, v186, v187
	v_fmamk_f32 v112, v112, 0x3a800000, v231
	v_rsq_f32_e32 v112, v112
	s_nop 0
	v_pk_mul_f32 v[190:191], v[108:109], v[112:113] op_sel_hi:[1,0]
	v_pk_mul_f32 v[192:193], v[110:111], v[112:113] op_sel_hi:[1,0]
	v_pk_mul_f32 v[188:189], v[190:191], v[190:191]
	v_pk_mul_f32 v[186:187], v[192:193], v[192:193]
	v_pk_mul_f32 v[196:197], v[106:107], v[112:113] op_sel_hi:[1,0]
	v_pk_mov_b32 v[194:195], v[188:189], v[186:187] op_sel:[1,0]
	v_mov_b32_e32 v189, v187
	v_pk_add_f32 v[186:187], v[194:195], v[188:189]
	v_pk_mul_f32 v[194:195], v[104:105], v[112:113] op_sel_hi:[1,0]
	v_pk_mul_f32 v[188:189], v[196:197], v[196:197]
	v_pk_mul_f32 v[198:199], v[194:195], v[194:195]
	v_pk_mul_f32 v[202:203], v[100:101], v[112:113] op_sel_hi:[1,0]
	v_pk_mov_b32 v[200:201], v[198:199], v[188:189] op_sel:[1,0]
	v_mov_b32_e32 v199, v189
	v_pk_mul_f32 v[224:225], v[102:103], v[112:113] op_sel_hi:[1,0]
	v_pk_add_f32 v[188:189], v[200:201], v[198:199]
	v_pk_mul_f32 v[198:199], v[224:225], v[224:225]
	v_pk_mul_f32 v[200:201], v[202:203], v[202:203]
	v_add_f32_e32 v213, v198, v199
	v_add_f32_e32 v211, v200, v201
	v_pk_mul_f32 v[198:199], v[96:97], v[112:113] op_sel_hi:[1,0]
	v_pk_mul_f32 v[200:201], v[98:99], v[112:113] op_sel_hi:[1,0]
	v_pk_add_f32 v[186:187], v[186:187], v[186:187] op_sel_hi:[0,1]
	v_pk_add_f32 v[188:189], v[188:189], v[188:189] op_sel_hi:[0,1]
	v_pk_mul_f32 v[226:227], v[200:201], v[200:201]
	v_pk_mul_f32 v[228:229], v[198:199], v[198:199]
	v_mov_b32_e32 v186, v226
	v_mov_b32_e32 v210, v228
	v_mov_b32_e32 v212, v229
	v_mov_b32_e32 v188, v227
	v_pk_add_f32 v[210:211], v[210:211], v[212:213]
	v_pk_add_f32 v[186:187], v[186:187], v[188:189]
	s_nop 0
	v_pk_add_f32 v[186:187], v[210:211], v[186:187]
	s_nop 0
	v_add_f32_e32 v112, v186, v187
	v_lshlrev_b64 v[186:187], 7, v[114:115]
	v_lshl_add_u64 v[226:227], v[170:171], 0, v[186:187]
	v_lshl_add_u64 v[228:229], v[172:173], 0, v[186:187]
	flat_load_dwordx4 v[186:189], v[226:227]
	flat_load_dwordx4 v[210:213], v[228:229]
	flat_load_dwordx4 v[246:249], v[226:227] offset:16
	flat_load_dwordx4 v[250:253], v[228:229] offset:16
	ds_bpermute_b32 v185, v209, v112
	s_waitcnt lgkmcnt(0)
	v_add_f32_e32 v112, v112, v185
	ds_bpermute_b32 v185, v222, v112
	s_waitcnt lgkmcnt(0)
	v_add_f32_e32 v112, v112, v185
	v_fmamk_f32 v112, v112, 0x3c800000, v231
	v_rsq_f32_e32 v112, v112
	s_nop 0
	v_pk_mul_f32 v[190:191], v[190:191], v[112:113] op_sel_hi:[1,0]
	v_pk_mul_f32 v[192:193], v[192:193], v[112:113] op_sel_hi:[1,0]
	v_pk_mul_f32 v[232:233], v[144:145], v[190:191]
	v_pk_mul_f32 v[190:191], v[202:203], v[112:113] op_sel_hi:[1,0]
	v_pk_mul_f32 v[242:243], v[146:147], v[192:193]
	v_pk_mul_f32 v[192:193], v[224:225], v[112:113] op_sel_hi:[1,0]
	v_pk_mul_f32 v[224:225], v[140:141], v[190:191]
	v_pk_mul_f32 v[202:203], v[142:143], v[192:193]
	v_pk_mul_f32 v[196:197], v[196:197], v[112:113] op_sel_hi:[1,0]
	v_pk_mul_f32 v[194:195], v[194:195], v[112:113] op_sel_hi:[1,0]
	s_waitcnt vmcnt(0)
	v_pk_mul_f32 v[192:193], v[210:211], v[224:225]
	v_pk_mul_f32 v[190:191], v[212:213], v[202:203]
	v_pk_fma_f32 v[192:193], v[186:187], v[232:233], v[192:193] neg_lo:[0,0,1] neg_hi:[0,0,1]
	v_pk_mul_f32 v[224:225], v[186:187], v[224:225]
	v_pk_mul_f32 v[186:187], v[188:189], v[202:203]
	v_pk_fma_f32 v[190:191], v[188:189], v[242:243], v[190:191] neg_lo:[0,0,1] neg_hi:[0,0,1]
	v_pk_fma_f32 v[186:187], v[212:213], v[242:243], v[186:187]
	v_pk_fma_f32 v[188:189], v[210:211], v[232:233], v[224:225]
	v_mov_b64_e32 v[210:211], v[246:247]
	v_mov_b64_e32 v[212:213], v[248:249]
	s_nop 0
	v_mov_b64_e32 v[224:225], v[250:251]
	v_mov_b64_e32 v[226:227], v[252:253]
	v_pk_mul_f32 v[202:203], v[136:137], v[194:195]
	v_pk_mul_f32 v[194:195], v[138:139], v[196:197]
	v_pk_mul_f32 v[196:197], v[198:199], v[112:113] op_sel_hi:[1,0]
	v_pk_mul_f32 v[198:199], v[200:201], v[112:113] op_sel_hi:[1,0]
	v_pk_mul_f32 v[196:197], v[132:133], v[196:197]
	v_pk_mul_f32 v[228:229], v[134:135], v[198:199]
	v_cndmask_b32_e64 v112, 0, 1, s[82:83]
	v_cmp_ne_u32_e64 s[10:11], 1, v112
	s_waitcnt vmcnt(0) lgkmcnt(0)
	v_pk_mul_f32 v[200:201], v[224:225], v[196:197]
	v_pk_mul_f32 v[198:199], v[226:227], v[228:229]
	v_pk_fma_f32 v[200:201], v[210:211], v[202:203], v[200:201] neg_lo:[0,0,1] neg_hi:[0,0,1]
	v_pk_mul_f32 v[196:197], v[210:211], v[196:197]
	v_pk_mul_f32 v[210:211], v[212:213], v[228:229]
	v_pk_fma_f32 v[198:199], v[212:213], v[194:195], v[198:199] neg_lo:[0,0,1] neg_hi:[0,0,1]
	v_pk_fma_f32 v[194:195], v[226:227], v[194:195], v[210:211]
	v_pk_fma_f32 v[196:197], v[224:225], v[202:203], v[196:197]
	s_cbranch_vccnz .LBB0_421
	v_pk_add_f32 v[162:163], v[162:163], v[190:191]
	v_pk_add_f32 v[160:161], v[160:161], v[192:193]
	v_pk_add_f32 v[158:159], v[158:159], v[198:199]
	v_pk_add_f32 v[156:157], v[156:157], v[200:201]
	v_pk_add_f32 v[154:155], v[154:155], v[186:187]
	v_pk_add_f32 v[152:153], v[152:153], v[188:189]
	v_pk_add_f32 v[150:151], v[150:151], v[194:195]
	v_pk_add_f32 v[148:149], v[148:149], v[196:197]
; __device__ __forceinline__ u32x4 pack8(const f32x4 a, const f32x4 b) { u32x4 w; w.x = cvt_pk_bf16(a[0], a[1]); w.y = cvt_pk_bf16(a[2], a[3]); w.z = cvt_pk_bf16(b[0], b[1]); w.w = cvt_pk_bf16(b[2], b[3]); return w; }
;     __device__ __forceinline__ void operator()(const f32x4 (&acc)[2][2][4][2], const Unit& u, int wr, int wc, int fr, int fq) const {
;     ...
;                 for (int m = 0; m < 4; ++m) { if (m == 0) asm volatile("" ::: "memory"); const int row = row0 + ai * HALF + m * 16; const float rs = rstd_of(ssq, row);
;                     f32x4 v[2][2]; float ss = 0.f;
; #pragma unroll
;                     for (int bj = 0; bj < 2; ++bj)
; #pragma unroll
;                         for (int n = 0; n < 2; ++n) { v[bj][n] = acc[ai][bj][m][n] * rs; const f32x4 q = v[bj][n] * v[bj][n]; ss += (q[0] + q[1]) + (q[2] + q[3]); }
;                     ss += __shfl_xor(ss, 16); ss += __shfl_xor(ss, 32);
;                     const float rn = __builtin_amdgcn_rsqf(ss * (1.0f / 64.0f) + 1e-6f);
;                     f32x4 o[2][2];
; #pragma unroll
;                     for (int n = 0; n < 2; ++n) { const f32x4 c = *(const f32x4*)(cosT + (size_t)row * 32 + 8 * fq + 4 * n), s = *(const f32x4*)(sinT + (size_t)row * 32 + 8 * fq + 4 * n);
;                         const f32x4 y1 = v[0][n] * rn * gv[0][n], y2 = v[1][n] * rn * gv[1][n];
;                         o[0][n] = y1 * c - y2 * s; o[1][n] = y2 * c + y1 * s; }
;                     if (dok) {
; #pragma unroll
;                         for (int bj = 0; bj < 2; ++bj)
; #pragma unroll
;                             for (int n = 0; n < 2; ++n) cs[bj][n] = cs[bj][n] + o[bj][n]; }
; #pragma unroll
;                     for (int bj = 0; bj < 2; ++bj) *(u32x4*)(ob + (size_t)row * 2816 + 32 * bj) = pack8(o[bj][0] * osc, o[bj][1] * osc); }
.LBB0_421:
	v_mov_b32_e32 v185, v184
	v_mad_i64_i32 v[202:203], s[12:13], v114, s92, v[180:181]
	v_mov_b32_e32 v114, v184
	v_mov_b32_e32 v115, v184
	v_pk_mul_f32 v[210:211], v[114:115], v[190:191]
	v_pk_mul_f32 v[190:191], v[184:185], v[192:193]
	v_pk_mul_f32 v[198:199], v[114:115], v[198:199]
	v_pk_mul_f32 v[192:193], v[184:185], v[200:201]
	v_cvt_pk_bf16_f32 v190, v190, v191
	v_cvt_pk_bf16_f32 v191, v210, v211
	v_cvt_pk_bf16_f32 v192, v192, v193
	v_cvt_pk_bf16_f32 v193, v198, v199
	flat_store_dwordx4 v[202:203], v[190:193]
	s_and_b64 vcc, exec, s[10:11]
	s_nop 0
	v_pk_mul_f32 v[190:191], v[114:115], v[186:187]
	v_pk_mul_f32 v[186:187], v[184:185], v[188:189]
	v_pk_mul_f32 v[192:193], v[114:115], v[194:195]
	v_pk_mul_f32 v[188:189], v[184:185], v[196:197]
	v_cvt_pk_bf16_f32 v186, v186, v187
	v_cvt_pk_bf16_f32 v187, v190, v191
	v_cvt_pk_bf16_f32 v188, v188, v189
	v_cvt_pk_bf16_f32 v189, v192, v193
	flat_store_dwordx4 v[202:203], v[186:189] offset:64
	s_nop 1
	v_or_b32_e32 v186, 32, v182
	v_ashrrev_i32_e32 v187, 31, v186
	v_lshl_add_u64 v[188:189], v[186:187], 4, s[18:19]
	flat_load_dwordx4 v[188:191], v[188:189]
	s_waitcnt vmcnt(0) lgkmcnt(0)
	v_mov_b32_e32 v192, v189
	v_mov_b32_e32 v193, v190
	v_mov_b32_e32 v189, v191
	v_pk_add_f32 v[188:189], v[192:193], v[188:189]
	s_nop 0
	v_add_f32_e32 v112, v188, v189
	v_fmamk_f32 v112, v112, 0x3a800000, v231
	v_rsq_f32_e32 v112, v112
	s_nop 0
	v_pk_mul_f32 v[192:193], v[92:93], v[112:113] op_sel_hi:[1,0]
	v_pk_mul_f32 v[194:195], v[94:95], v[112:113] op_sel_hi:[1,0]
	v_pk_mul_f32 v[190:191], v[192:193], v[192:193]
	v_pk_mul_f32 v[188:189], v[194:195], v[194:195]
	v_pk_mul_f32 v[198:199], v[90:91], v[112:113] op_sel_hi:[1,0]
	v_pk_mov_b32 v[196:197], v[190:191], v[188:189] op_sel:[1,0]
	v_mov_b32_e32 v191, v189
	v_pk_add_f32 v[188:189], v[196:197], v[190:191]
	v_pk_mul_f32 v[196:197], v[88:89], v[112:113] op_sel_hi:[1,0]
	v_pk_mul_f32 v[190:191], v[198:199], v[198:199]
	v_pk_mul_f32 v[200:201], v[196:197], v[196:197]
	v_pk_mul_f32 v[224:225], v[84:85], v[112:113] op_sel_hi:[1,0]
	v_pk_mov_b32 v[202:203], v[200:201], v[190:191] op_sel:[1,0]
	v_mov_b32_e32 v201, v191
	v_pk_mul_f32 v[226:227], v[86:87], v[112:113] op_sel_hi:[1,0]
	v_pk_add_f32 v[190:191], v[202:203], v[200:201]
	v_pk_mul_f32 v[200:201], v[226:227], v[226:227]
	v_pk_mul_f32 v[202:203], v[224:225], v[224:225]
	v_add_f32_e32 v213, v200, v201
	v_add_f32_e32 v211, v202, v203
	v_pk_mul_f32 v[200:201], v[80:81], v[112:113] op_sel_hi:[1,0]
	v_pk_mul_f32 v[202:203], v[82:83], v[112:113] op_sel_hi:[1,0]
	v_pk_add_f32 v[188:189], v[188:189], v[188:189] op_sel_hi:[0,1]
	v_pk_add_f32 v[190:191], v[190:191], v[190:191] op_sel_hi:[0,1]
	v_pk_mul_f32 v[228:229], v[202:203], v[202:203]
	v_pk_mul_f32 v[232:233], v[200:201], v[200:201]
	v_mov_b32_e32 v188, v228
	v_mov_b32_e32 v210, v232
	v_mov_b32_e32 v212, v233
	v_mov_b32_e32 v190, v229
	v_pk_add_f32 v[210:211], v[210:211], v[212:213]
	v_pk_add_f32 v[188:189], v[188:189], v[190:191]
	s_nop 0
	v_pk_add_f32 v[188:189], v[210:211], v[188:189]
	s_nop 0
	v_add_f32_e32 v112, v188, v189
	ds_bpermute_b32 v188, v209, v112
	s_waitcnt lgkmcnt(0)
	v_add_f32_e32 v112, v112, v188
	ds_bpermute_b32 v188, v222, v112
	s_waitcnt lgkmcnt(0)
	v_add_f32_e32 v112, v112, v188
	v_lshlrev_b64 v[188:189], 7, v[186:187]
	v_lshl_add_u64 v[228:229], v[170:171], 0, v[188:189]
	v_lshl_add_u64 v[232:233], v[172:173], 0, v[188:189]
	flat_load_dwordx4 v[188:191], v[228:229]
	flat_load_dwordx4 v[210:213], v[232:233]
	flat_load_dwordx4 v[246:249], v[228:229] offset:16
	flat_load_dwordx4 v[250:253], v[232:233] offset:16
	v_fmamk_f32 v112, v112, 0x3c800000, v231
	v_rsq_f32_e32 v112, v112
	s_nop 0
	v_pk_mul_f32 v[192:193], v[192:193], v[112:113] op_sel_hi:[1,0]
	v_pk_mul_f32 v[194:195], v[194:195], v[112:113] op_sel_hi:[1,0]
	v_pk_mul_f32 v[242:243], v[144:145], v[192:193]
	v_pk_mul_f32 v[192:193], v[224:225], v[112:113] op_sel_hi:[1,0]
	v_pk_mul_f32 v[244:245], v[146:147], v[194:195]
	v_pk_mul_f32 v[194:195], v[226:227], v[112:113] op_sel_hi:[1,0]
	v_pk_mul_f32 v[226:227], v[140:141], v[192:193]
	v_pk_mul_f32 v[224:225], v[142:143], v[194:195]
	v_pk_mul_f32 v[198:199], v[198:199], v[112:113] op_sel_hi:[1,0]
	v_pk_mul_f32 v[196:197], v[196:197], v[112:113] op_sel_hi:[1,0]
	s_waitcnt vmcnt(0) lgkmcnt(0)
	v_pk_mul_f32 v[194:195], v[210:211], v[226:227]
	v_pk_mul_f32 v[192:193], v[212:213], v[224:225]
	v_pk_fma_f32 v[194:195], v[188:189], v[242:243], v[194:195] neg_lo:[0,0,1] neg_hi:[0,0,1]
	v_pk_mul_f32 v[226:227], v[188:189], v[226:227]
	v_pk_mul_f32 v[188:189], v[190:191], v[224:225]
	v_pk_fma_f32 v[192:193], v[190:191], v[244:245], v[192:193] neg_lo:[0,0,1] neg_hi:[0,0,1]
	v_pk_fma_f32 v[188:189], v[212:213], v[244:245], v[188:189]
	v_pk_fma_f32 v[190:191], v[210:211], v[242:243], v[226:227]
	v_mov_b64_e32 v[210:211], v[246:247]
	v_mov_b64_e32 v[212:213], v[248:249]
	v_mov_b64_e32 v[224:225], v[250:251]
	v_mov_b64_e32 v[226:227], v[252:253]
	v_pk_mul_f32 v[228:229], v[136:137], v[196:197]
	v_pk_mul_f32 v[196:197], v[138:139], v[198:199]
	v_pk_mul_f32 v[198:199], v[200:201], v[112:113] op_sel_hi:[1,0]
	v_pk_mul_f32 v[200:201], v[202:203], v[112:113] op_sel_hi:[1,0]
	v_pk_mul_f32 v[198:199], v[132:133], v[198:199]
	v_pk_mul_f32 v[232:233], v[134:135], v[200:201]
	s_waitcnt vmcnt(0) lgkmcnt(0)
	v_pk_mul_f32 v[202:203], v[224:225], v[198:199]
	v_pk_mul_f32 v[200:201], v[226:227], v[232:233]
	v_pk_fma_f32 v[202:203], v[210:211], v[228:229], v[202:203] neg_lo:[0,0,1] neg_hi:[0,0,1]
	v_pk_mul_f32 v[198:199], v[210:211], v[198:199]
	v_pk_mul_f32 v[210:211], v[212:213], v[232:233]
	v_pk_fma_f32 v[200:201], v[212:213], v[196:197], v[200:201] neg_lo:[0,0,1] neg_hi:[0,0,1]
	v_pk_fma_f32 v[196:197], v[226:227], v[196:197], v[210:211]
	v_pk_fma_f32 v[198:199], v[224:225], v[228:229], v[198:199]
	s_cbranch_vccnz .LBB0_423
	v_pk_add_f32 v[162:163], v[162:163], v[192:193]
	v_pk_add_f32 v[160:161], v[160:161], v[194:195]
	v_pk_add_f32 v[158:159], v[158:159], v[200:201]
	v_pk_add_f32 v[156:157], v[156:157], v[202:203]
	v_pk_add_f32 v[154:155], v[154:155], v[188:189]
	v_pk_add_f32 v[152:153], v[152:153], v[190:191]
	v_pk_add_f32 v[150:151], v[150:151], v[196:197]
	v_pk_add_f32 v[148:149], v[148:149], v[198:199]
; __device__ __forceinline__ u32x4 pack8(const f32x4 a, const f32x4 b) { u32x4 w; w.x = cvt_pk_bf16(a[0], a[1]); w.y = cvt_pk_bf16(a[2], a[3]); w.z = cvt_pk_bf16(b[0], b[1]); w.w = cvt_pk_bf16(b[2], b[3]); return w; }
;     __device__ __forceinline__ void operator()(const f32x4 (&acc)[2][2][4][2], const Unit& u, int wr, int wc, int fr, int fq) const {
;     ...
;                 for (int m = 0; m < 4; ++m) { if (m == 0) asm volatile("" ::: "memory"); const int row = row0 + ai * HALF + m * 16; const float rs = rstd_of(ssq, row);
;                     f32x4 v[2][2]; float ss = 0.f;
; #pragma unroll
;                     for (int bj = 0; bj < 2; ++bj)
; #pragma unroll
;                         for (int n = 0; n < 2; ++n) { v[bj][n] = acc[ai][bj][m][n] * rs; const f32x4 q = v[bj][n] * v[bj][n]; ss += (q[0] + q[1]) + (q[2] + q[3]); }
;                     ss += __shfl_xor(ss, 16); ss += __shfl_xor(ss, 32);
;                     const float rn = __builtin_amdgcn_rsqf(ss * (1.0f / 64.0f) + 1e-6f);
;                     f32x4 o[2][2];
; #pragma unroll
;                     for (int n = 0; n < 2; ++n) { const f32x4 c = *(const f32x4*)(cosT + (size_t)row * 32 + 8 * fq + 4 * n), s = *(const f32x4*)(sinT + (size_t)row * 32 + 8 * fq + 4 * n);
;                         const f32x4 y1 = v[0][n] * rn * gv[0][n], y2 = v[1][n] * rn * gv[1][n];
;                         o[0][n] = y1 * c - y2 * s; o[1][n] = y2 * c + y1 * s; }
;                     if (dok) {
; #pragma unroll
;                         for (int bj = 0; bj < 2; ++bj)
; #pragma unroll
;                             for (int n = 0; n < 2; ++n) cs[bj][n] = cs[bj][n] + o[bj][n]; }
; #pragma unroll
;                     for (int bj = 0; bj < 2; ++bj) *(u32x4*)(ob + (size_t)row * 2816 + 32 * bj) = pack8(o[bj][0] * osc, o[bj][1] * osc); }
.LBB0_423:
	v_mad_i64_i32 v[210:211], s[12:13], v186, s92, v[180:181]
	v_pk_mul_f32 v[186:187], v[114:115], v[192:193]
	v_pk_mul_f32 v[192:193], v[184:185], v[194:195]
	v_pk_mul_f32 v[200:201], v[114:115], v[200:201]
	v_cvt_pk_bf16_f32 v192, v192, v193
	v_cvt_pk_bf16_f32 v193, v186, v187
	v_pk_mul_f32 v[188:189], v[114:115], v[188:189]
	v_pk_mul_f32 v[186:187], v[184:185], v[190:191]
	v_pk_mul_f32 v[114:115], v[114:115], v[196:197]
	v_pk_mul_f32 v[194:195], v[184:185], v[202:203]
	v_pk_mul_f32 v[190:191], v[184:185], v[198:199]
	v_cvt_pk_bf16_f32 v186, v186, v187
	v_cvt_pk_bf16_f32 v187, v188, v189
	v_cvt_pk_bf16_f32 v189, v114, v115
	v_or_b32_e32 v114, 48, v182
	v_cvt_pk_bf16_f32 v194, v194, v195
	v_cvt_pk_bf16_f32 v195, v200, v201
	v_cvt_pk_bf16_f32 v188, v190, v191
	v_ashrrev_i32_e32 v115, 31, v114
	flat_store_dwordx4 v[210:211], v[192:195]
	flat_store_dwordx4 v[210:211], v[186:189] offset:64
	s_and_b64 vcc, exec, s[10:11]
	s_nop 0
	v_lshl_add_u64 v[186:187], v[114:115], 4, s[18:19]
	flat_load_dwordx4 v[186:189], v[186:187]
	s_waitcnt vmcnt(0) lgkmcnt(0)
	v_mov_b32_e32 v190, v187
	v_mov_b32_e32 v191, v188
	v_mov_b32_e32 v187, v189
	v_pk_add_f32 v[186:187], v[190:191], v[186:187]
	s_nop 0
	v_add_f32_e32 v112, v186, v187
	v_fmamk_f32 v112, v112, 0x3a800000, v231
	v_rsq_f32_e32 v112, v112
	s_nop 0
	v_pk_mul_f32 v[190:191], v[76:77], v[112:113] op_sel_hi:[1,0]
	v_pk_mul_f32 v[192:193], v[78:79], v[112:113] op_sel_hi:[1,0]
	v_pk_mul_f32 v[188:189], v[190:191], v[190:191]
	v_pk_mul_f32 v[186:187], v[192:193], v[192:193]
	v_pk_mul_f32 v[196:197], v[74:75], v[112:113] op_sel_hi:[1,0]
	v_pk_mov_b32 v[194:195], v[188:189], v[186:187] op_sel:[1,0]
	v_mov_b32_e32 v189, v187
	v_pk_add_f32 v[186:187], v[194:195], v[188:189]
	v_pk_mul_f32 v[194:195], v[72:73], v[112:113] op_sel_hi:[1,0]
	v_pk_mul_f32 v[188:189], v[196:197], v[196:197]
	v_pk_mul_f32 v[198:199], v[194:195], v[194:195]
	v_pk_mul_f32 v[202:203], v[68:69], v[112:113] op_sel_hi:[1,0]
	v_pk_mov_b32 v[200:201], v[198:199], v[188:189] op_sel:[1,0]
	v_mov_b32_e32 v199, v189
	v_pk_mul_f32 v[224:225], v[70:71], v[112:113] op_sel_hi:[1,0]
	v_pk_add_f32 v[188:189], v[200:201], v[198:199]
	v_pk_mul_f32 v[198:199], v[224:225], v[224:225]
	v_pk_mul_f32 v[200:201], v[202:203], v[202:203]
	v_add_f32_e32 v213, v198, v199
	v_add_f32_e32 v211, v200, v201
	v_pk_mul_f32 v[198:199], v[64:65], v[112:113] op_sel_hi:[1,0]
	v_pk_mul_f32 v[200:201], v[66:67], v[112:113] op_sel_hi:[1,0]
	v_pk_add_f32 v[186:187], v[186:187], v[186:187] op_sel_hi:[0,1]
	v_pk_add_f32 v[188:189], v[188:189], v[188:189] op_sel_hi:[0,1]
	v_pk_mul_f32 v[226:227], v[200:201], v[200:201]
	v_pk_mul_f32 v[228:229], v[198:199], v[198:199]
	v_mov_b32_e32 v186, v226
	v_mov_b32_e32 v210, v228
	v_mov_b32_e32 v212, v229
	v_mov_b32_e32 v188, v227
	v_pk_add_f32 v[210:211], v[210:211], v[212:213]
	v_pk_add_f32 v[186:187], v[186:187], v[188:189]
	s_nop 0
	v_pk_add_f32 v[186:187], v[210:211], v[186:187]
	s_nop 0
	v_add_f32_e32 v112, v186, v187
	ds_bpermute_b32 v186, v209, v112
	s_waitcnt lgkmcnt(0)
	v_add_f32_e32 v112, v112, v186
	ds_bpermute_b32 v186, v222, v112
	s_waitcnt lgkmcnt(0)
	v_add_f32_e32 v112, v112, v186
	v_lshlrev_b64 v[186:187], 7, v[114:115]
	v_lshl_add_u64 v[226:227], v[170:171], 0, v[186:187]
	v_lshl_add_u64 v[228:229], v[172:173], 0, v[186:187]
	flat_load_dwordx4 v[186:189], v[226:227]
	flat_load_dwordx4 v[210:213], v[228:229]
	flat_load_dwordx4 v[246:249], v[226:227] offset:16
	flat_load_dwordx4 v[250:253], v[228:229] offset:16
	v_fmamk_f32 v112, v112, 0x3c800000, v231
	v_rsq_f32_e32 v112, v112
	s_nop 0
	v_pk_mul_f32 v[190:191], v[190:191], v[112:113] op_sel_hi:[1,0]
	v_pk_mul_f32 v[192:193], v[192:193], v[112:113] op_sel_hi:[1,0]
	v_pk_mul_f32 v[232:233], v[144:145], v[190:191]
	v_pk_mul_f32 v[190:191], v[202:203], v[112:113] op_sel_hi:[1,0]
	v_pk_mul_f32 v[242:243], v[146:147], v[192:193]
	v_pk_mul_f32 v[192:193], v[224:225], v[112:113] op_sel_hi:[1,0]
	v_pk_mul_f32 v[224:225], v[140:141], v[190:191]
	v_pk_mul_f32 v[202:203], v[142:143], v[192:193]
	v_pk_mul_f32 v[196:197], v[196:197], v[112:113] op_sel_hi:[1,0]
	v_pk_mul_f32 v[194:195], v[194:195], v[112:113] op_sel_hi:[1,0]
	s_waitcnt vmcnt(0) lgkmcnt(0)
	v_pk_mul_f32 v[192:193], v[210:211], v[224:225]
	v_pk_mul_f32 v[190:191], v[212:213], v[202:203]
	v_pk_fma_f32 v[192:193], v[186:187], v[232:233], v[192:193] neg_lo:[0,0,1] neg_hi:[0,0,1]
	v_pk_mul_f32 v[224:225], v[186:187], v[224:225]
	v_pk_mul_f32 v[186:187], v[188:189], v[202:203]
	v_pk_fma_f32 v[190:191], v[188:189], v[242:243], v[190:191] neg_lo:[0,0,1] neg_hi:[0,0,1]
	v_pk_fma_f32 v[186:187], v[212:213], v[242:243], v[186:187]
	v_pk_fma_f32 v[188:189], v[210:211], v[232:233], v[224:225]
	v_mov_b64_e32 v[210:211], v[246:247]
	v_mov_b64_e32 v[212:213], v[248:249]
	s_nop 0
	v_mov_b64_e32 v[224:225], v[250:251]
	v_mov_b64_e32 v[226:227], v[252:253]
	v_pk_mul_f32 v[202:203], v[136:137], v[194:195]
	v_pk_mul_f32 v[194:195], v[138:139], v[196:197]
	v_pk_mul_f32 v[196:197], v[198:199], v[112:113] op_sel_hi:[1,0]
	v_pk_mul_f32 v[198:199], v[200:201], v[112:113] op_sel_hi:[1,0]
	v_pk_mul_f32 v[196:197], v[132:133], v[196:197]
	v_pk_mul_f32 v[228:229], v[134:135], v[198:199]
	s_waitcnt vmcnt(0) lgkmcnt(0)
	v_pk_mul_f32 v[200:201], v[224:225], v[196:197]
	v_pk_mul_f32 v[198:199], v[226:227], v[228:229]
	v_pk_fma_f32 v[200:201], v[210:211], v[202:203], v[200:201] neg_lo:[0,0,1] neg_hi:[0,0,1]
	v_pk_mul_f32 v[196:197], v[210:211], v[196:197]
	v_pk_mul_f32 v[210:211], v[212:213], v[228:229]
	v_pk_fma_f32 v[198:199], v[212:213], v[194:195], v[198:199] neg_lo:[0,0,1] neg_hi:[0,0,1]
	v_pk_fma_f32 v[194:195], v[226:227], v[194:195], v[210:211]
	v_pk_fma_f32 v[196:197], v[224:225], v[202:203], v[196:197]
	s_cbranch_vccnz .LBB0_425
	v_pk_add_f32 v[162:163], v[162:163], v[190:191]
	v_pk_add_f32 v[160:161], v[160:161], v[192:193]
	v_pk_add_f32 v[158:159], v[158:159], v[198:199]
	v_pk_add_f32 v[156:157], v[156:157], v[200:201]
	v_pk_add_f32 v[154:155], v[154:155], v[186:187]
	v_pk_add_f32 v[152:153], v[152:153], v[188:189]
	v_pk_add_f32 v[150:151], v[150:151], v[194:195]
	v_pk_add_f32 v[148:149], v[148:149], v[196:197]
; __device__ __forceinline__ u32x4 pack8(const f32x4 a, const f32x4 b) { u32x4 w; w.x = cvt_pk_bf16(a[0], a[1]); w.y = cvt_pk_bf16(a[2], a[3]); w.z = cvt_pk_bf16(b[0], b[1]); w.w = cvt_pk_bf16(b[2], b[3]); return w; }
;     __device__ __forceinline__ void operator()(const f32x4 (&acc)[2][2][4][2], const Unit& u, int wr, int wc, int fr, int fq) const {
;     ...
;                 for (int m = 0; m < 4; ++m) { if (m == 0) asm volatile("" ::: "memory"); const int row = row0 + ai * HALF + m * 16; const float rs = rstd_of(ssq, row);
;                     f32x4 v[2][2]; float ss = 0.f;
; #pragma unroll
;                     for (int bj = 0; bj < 2; ++bj)
; #pragma unroll
;                         for (int n = 0; n < 2; ++n) { v[bj][n] = acc[ai][bj][m][n] * rs; const f32x4 q = v[bj][n] * v[bj][n]; ss += (q[0] + q[1]) + (q[2] + q[3]); }
;                     ss += __shfl_xor(ss, 16); ss += __shfl_xor(ss, 32);
;                     const float rn = __builtin_amdgcn_rsqf(ss * (1.0f / 64.0f) + 1e-6f);
;                     f32x4 o[2][2];
; #pragma unroll
;                     for (int n = 0; n < 2; ++n) { const f32x4 c = *(const f32x4*)(cosT + (size_t)row * 32 + 8 * fq + 4 * n), s = *(const f32x4*)(sinT + (size_t)row * 32 + 8 * fq + 4 * n);
;                         const f32x4 y1 = v[0][n] * rn * gv[0][n], y2 = v[1][n] * rn * gv[1][n];
;                         o[0][n] = y1 * c - y2 * s; o[1][n] = y2 * c + y1 * s; }
;                     if (dok) {
; #pragma unroll
;                         for (int bj = 0; bj < 2; ++bj)
; #pragma unroll
;                             for (int n = 0; n < 2; ++n) cs[bj][n] = cs[bj][n] + o[bj][n]; }
; #pragma unroll
;                     for (int bj = 0; bj < 2; ++bj) *(u32x4*)(ob + (size_t)row * 2816 + 32 * bj) = pack8(o[bj][0] * osc, o[bj][1] * osc); }
.LBB0_425:
	v_mad_i64_i32 v[202:203], s[12:13], v114, s92, v[180:181]
	v_mov_b32_e32 v114, v184
	v_mov_b32_e32 v115, v184
	v_pk_mul_f32 v[210:211], v[114:115], v[190:191]
	v_pk_mul_f32 v[190:191], v[184:185], v[192:193]
	v_pk_mul_f32 v[198:199], v[114:115], v[198:199]
	v_pk_mul_f32 v[192:193], v[184:185], v[200:201]
	v_cvt_pk_bf16_f32 v190, v190, v191
	v_cvt_pk_bf16_f32 v191, v210, v211
	v_cvt_pk_bf16_f32 v192, v192, v193
	v_cvt_pk_bf16_f32 v193, v198, v199
	flat_store_dwordx4 v[202:203], v[190:193]
	s_and_b64 vcc, exec, s[10:11]
	s_nop 0
	v_pk_mul_f32 v[190:191], v[114:115], v[186:187]
	v_pk_mul_f32 v[186:187], v[184:185], v[188:189]
	v_pk_mul_f32 v[192:193], v[114:115], v[194:195]
	v_pk_mul_f32 v[188:189], v[184:185], v[196:197]
	v_cvt_pk_bf16_f32 v186, v186, v187
	v_cvt_pk_bf16_f32 v187, v190, v191
	v_cvt_pk_bf16_f32 v188, v188, v189
	v_cvt_pk_bf16_f32 v189, v192, v193
	flat_store_dwordx4 v[202:203], v[186:189] offset:64
	s_nop 1
	v_add_u32_e32 v186, 0x80, v182
	v_ashrrev_i32_e32 v187, 31, v186
	v_lshl_add_u64 v[188:189], v[186:187], 4, s[18:19]
	flat_load_dwordx4 v[188:191], v[188:189]
	s_waitcnt vmcnt(0) lgkmcnt(0)
	v_mov_b32_e32 v192, v189
	v_mov_b32_e32 v193, v190
	v_mov_b32_e32 v189, v191
	v_pk_add_f32 v[188:189], v[192:193], v[188:189]
	s_nop 0
	v_add_f32_e32 v112, v188, v189
	v_fmamk_f32 v112, v112, 0x3a800000, v231
	v_rsq_f32_e32 v112, v112
	s_nop 0
	v_pk_mul_f32 v[192:193], v[60:61], v[112:113] op_sel_hi:[1,0]
	v_pk_mul_f32 v[194:195], v[62:63], v[112:113] op_sel_hi:[1,0]
	v_pk_mul_f32 v[190:191], v[192:193], v[192:193]
	v_pk_mul_f32 v[188:189], v[194:195], v[194:195]
	v_pk_mul_f32 v[198:199], v[58:59], v[112:113] op_sel_hi:[1,0]
	v_pk_mov_b32 v[196:197], v[190:191], v[188:189] op_sel:[1,0]
	v_mov_b32_e32 v191, v189
	v_pk_add_f32 v[188:189], v[196:197], v[190:191]
	v_pk_mul_f32 v[196:197], v[56:57], v[112:113] op_sel_hi:[1,0]
	v_pk_mul_f32 v[190:191], v[198:199], v[198:199]
	v_pk_mul_f32 v[200:201], v[196:197], v[196:197]
	v_pk_mul_f32 v[224:225], v[52:53], v[112:113] op_sel_hi:[1,0]
	v_pk_mov_b32 v[202:203], v[200:201], v[190:191] op_sel:[1,0]
	v_mov_b32_e32 v201, v191
	v_pk_mul_f32 v[226:227], v[54:55], v[112:113] op_sel_hi:[1,0]
	v_pk_add_f32 v[190:191], v[202:203], v[200:201]
	v_pk_mul_f32 v[200:201], v[226:227], v[226:227]
	v_pk_mul_f32 v[202:203], v[224:225], v[224:225]
	v_add_f32_e32 v213, v200, v201
	v_add_f32_e32 v211, v202, v203
	v_pk_mul_f32 v[200:201], v[48:49], v[112:113] op_sel_hi:[1,0]
	v_pk_mul_f32 v[202:203], v[50:51], v[112:113] op_sel_hi:[1,0]
	v_pk_add_f32 v[188:189], v[188:189], v[188:189] op_sel_hi:[0,1]
	v_pk_add_f32 v[190:191], v[190:191], v[190:191] op_sel_hi:[0,1]
	v_pk_mul_f32 v[228:229], v[202:203], v[202:203]
	v_pk_mul_f32 v[232:233], v[200:201], v[200:201]
	v_mov_b32_e32 v188, v228
	v_mov_b32_e32 v210, v232
	v_mov_b32_e32 v212, v233
	v_mov_b32_e32 v190, v229
	v_pk_add_f32 v[210:211], v[210:211], v[212:213]
	v_pk_add_f32 v[188:189], v[188:189], v[190:191]
	s_nop 0
	v_pk_add_f32 v[188:189], v[210:211], v[188:189]
	s_nop 0
	v_add_f32_e32 v112, v188, v189
	ds_bpermute_b32 v188, v209, v112
	s_waitcnt lgkmcnt(0)
	v_add_f32_e32 v112, v112, v188
	ds_bpermute_b32 v188, v222, v112
	s_waitcnt lgkmcnt(0)
	v_add_f32_e32 v112, v112, v188
	v_lshlrev_b64 v[188:189], 7, v[186:187]
	v_lshl_add_u64 v[228:229], v[170:171], 0, v[188:189]
	v_lshl_add_u64 v[232:233], v[172:173], 0, v[188:189]
	flat_load_dwordx4 v[188:191], v[228:229]
	flat_load_dwordx4 v[210:213], v[232:233]
	flat_load_dwordx4 v[246:249], v[228:229] offset:16
	flat_load_dwordx4 v[250:253], v[232:233] offset:16
	v_fmamk_f32 v112, v112, 0x3c800000, v231
	v_rsq_f32_e32 v112, v112
	s_nop 0
	v_pk_mul_f32 v[192:193], v[192:193], v[112:113] op_sel_hi:[1,0]
	v_pk_mul_f32 v[194:195], v[194:195], v[112:113] op_sel_hi:[1,0]
	v_pk_mul_f32 v[242:243], v[144:145], v[192:193]
	v_pk_mul_f32 v[192:193], v[224:225], v[112:113] op_sel_hi:[1,0]
	v_pk_mul_f32 v[244:245], v[146:147], v[194:195]
	v_pk_mul_f32 v[194:195], v[226:227], v[112:113] op_sel_hi:[1,0]
	v_pk_mul_f32 v[226:227], v[140:141], v[192:193]
	v_pk_mul_f32 v[224:225], v[142:143], v[194:195]
	v_pk_mul_f32 v[198:199], v[198:199], v[112:113] op_sel_hi:[1,0]
	v_pk_mul_f32 v[196:197], v[196:197], v[112:113] op_sel_hi:[1,0]
	s_waitcnt vmcnt(0) lgkmcnt(0)
	v_pk_mul_f32 v[194:195], v[210:211], v[226:227]
	v_pk_mul_f32 v[192:193], v[212:213], v[224:225]
	v_pk_fma_f32 v[194:195], v[188:189], v[242:243], v[194:195] neg_lo:[0,0,1] neg_hi:[0,0,1]
	v_pk_mul_f32 v[226:227], v[188:189], v[226:227]
	v_pk_mul_f32 v[188:189], v[190:191], v[224:225]
	v_pk_fma_f32 v[192:193], v[190:191], v[244:245], v[192:193] neg_lo:[0,0,1] neg_hi:[0,0,1]
	v_pk_fma_f32 v[188:189], v[212:213], v[244:245], v[188:189]
	v_pk_fma_f32 v[190:191], v[210:211], v[242:243], v[226:227]
	v_mov_b64_e32 v[210:211], v[246:247]
	v_mov_b64_e32 v[212:213], v[248:249]
	v_mov_b64_e32 v[224:225], v[250:251]
	v_mov_b64_e32 v[226:227], v[252:253]
	v_pk_mul_f32 v[228:229], v[136:137], v[196:197]
	v_pk_mul_f32 v[196:197], v[138:139], v[198:199]
	v_pk_mul_f32 v[198:199], v[200:201], v[112:113] op_sel_hi:[1,0]
	v_pk_mul_f32 v[200:201], v[202:203], v[112:113] op_sel_hi:[1,0]
	v_pk_mul_f32 v[198:199], v[132:133], v[198:199]
	v_pk_mul_f32 v[232:233], v[134:135], v[200:201]
	s_waitcnt vmcnt(0) lgkmcnt(0)
	v_pk_mul_f32 v[202:203], v[224:225], v[198:199]
	v_pk_mul_f32 v[200:201], v[226:227], v[232:233]
	v_pk_fma_f32 v[202:203], v[210:211], v[228:229], v[202:203] neg_lo:[0,0,1] neg_hi:[0,0,1]
	v_pk_mul_f32 v[198:199], v[210:211], v[198:199]
	v_pk_mul_f32 v[210:211], v[212:213], v[232:233]
	v_pk_fma_f32 v[200:201], v[212:213], v[196:197], v[200:201] neg_lo:[0,0,1] neg_hi:[0,0,1]
	v_pk_fma_f32 v[196:197], v[226:227], v[196:197], v[210:211]
	v_pk_fma_f32 v[198:199], v[224:225], v[228:229], v[198:199]
	s_cbranch_vccnz .LBB0_427
	v_pk_add_f32 v[162:163], v[162:163], v[192:193]
	v_pk_add_f32 v[160:161], v[160:161], v[194:195]
	v_pk_add_f32 v[158:159], v[158:159], v[200:201]
	v_pk_add_f32 v[156:157], v[156:157], v[202:203]
	v_pk_add_f32 v[154:155], v[154:155], v[188:189]
	v_pk_add_f32 v[152:153], v[152:153], v[190:191]
	v_pk_add_f32 v[150:151], v[150:151], v[196:197]
	v_pk_add_f32 v[148:149], v[148:149], v[198:199]
; __device__ __forceinline__ u32x4 pack8(const f32x4 a, const f32x4 b) { u32x4 w; w.x = cvt_pk_bf16(a[0], a[1]); w.y = cvt_pk_bf16(a[2], a[3]); w.z = cvt_pk_bf16(b[0], b[1]); w.w = cvt_pk_bf16(b[2], b[3]); return w; }
;     __device__ __forceinline__ void operator()(const f32x4 (&acc)[2][2][4][2], const Unit& u, int wr, int wc, int fr, int fq) const {
;     ...
;                 for (int m = 0; m < 4; ++m) { if (m == 0) asm volatile("" ::: "memory"); const int row = row0 + ai * HALF + m * 16; const float rs = rstd_of(ssq, row);
;                     f32x4 v[2][2]; float ss = 0.f;
; #pragma unroll
;                     for (int bj = 0; bj < 2; ++bj)
; #pragma unroll
;                         for (int n = 0; n < 2; ++n) { v[bj][n] = acc[ai][bj][m][n] * rs; const f32x4 q = v[bj][n] * v[bj][n]; ss += (q[0] + q[1]) + (q[2] + q[3]); }
;                     ss += __shfl_xor(ss, 16); ss += __shfl_xor(ss, 32);
;                     const float rn = __builtin_amdgcn_rsqf(ss * (1.0f / 64.0f) + 1e-6f);
;                     f32x4 o[2][2];
; #pragma unroll
;                     for (int n = 0; n < 2; ++n) { const f32x4 c = *(const f32x4*)(cosT + (size_t)row * 32 + 8 * fq + 4 * n), s = *(const f32x4*)(sinT + (size_t)row * 32 + 8 * fq + 4 * n);
;                         const f32x4 y1 = v[0][n] * rn * gv[0][n], y2 = v[1][n] * rn * gv[1][n];
;                         o[0][n] = y1 * c - y2 * s; o[1][n] = y2 * c + y1 * s; }
;                     if (dok) {
; #pragma unroll
;                         for (int bj = 0; bj < 2; ++bj)
; #pragma unroll
;                             for (int n = 0; n < 2; ++n) cs[bj][n] = cs[bj][n] + o[bj][n]; }
; #pragma unroll
;                     for (int bj = 0; bj < 2; ++bj) *(u32x4*)(ob + (size_t)row * 2816 + 32 * bj) = pack8(o[bj][0] * osc, o[bj][1] * osc); }
.LBB0_427:
	v_mad_i64_i32 v[210:211], s[12:13], v186, s92, v[180:181]
	v_pk_mul_f32 v[186:187], v[114:115], v[192:193]
	v_pk_mul_f32 v[192:193], v[184:185], v[194:195]
	v_pk_mul_f32 v[200:201], v[114:115], v[200:201]
	v_cvt_pk_bf16_f32 v192, v192, v193
	v_cvt_pk_bf16_f32 v193, v186, v187
	v_pk_mul_f32 v[188:189], v[114:115], v[188:189]
	v_pk_mul_f32 v[186:187], v[184:185], v[190:191]
	v_pk_mul_f32 v[114:115], v[114:115], v[196:197]
	v_pk_mul_f32 v[194:195], v[184:185], v[202:203]
	v_pk_mul_f32 v[190:191], v[184:185], v[198:199]
	v_cvt_pk_bf16_f32 v186, v186, v187
	v_cvt_pk_bf16_f32 v187, v188, v189
	v_cvt_pk_bf16_f32 v189, v114, v115
	v_add_u32_e32 v114, 0x90, v182
	v_cvt_pk_bf16_f32 v194, v194, v195
	v_cvt_pk_bf16_f32 v195, v200, v201
	v_cvt_pk_bf16_f32 v188, v190, v191
	v_ashrrev_i32_e32 v115, 31, v114
	flat_store_dwordx4 v[210:211], v[192:195]
	flat_store_dwordx4 v[210:211], v[186:189] offset:64
	s_and_b64 vcc, exec, s[10:11]
	s_nop 0
	v_lshl_add_u64 v[186:187], v[114:115], 4, s[18:19]
	flat_load_dwordx4 v[186:189], v[186:187]
	s_waitcnt vmcnt(0) lgkmcnt(0)
	v_mov_b32_e32 v190, v187
	v_mov_b32_e32 v191, v188
	v_mov_b32_e32 v187, v189
	v_pk_add_f32 v[186:187], v[190:191], v[186:187]
	s_nop 0
	v_add_f32_e32 v112, v186, v187
	v_fmamk_f32 v112, v112, 0x3a800000, v231
	v_rsq_f32_e32 v112, v112
	s_nop 0
	v_pk_mul_f32 v[190:191], v[44:45], v[112:113] op_sel_hi:[1,0]
	v_pk_mul_f32 v[192:193], v[46:47], v[112:113] op_sel_hi:[1,0]
	v_pk_mul_f32 v[188:189], v[190:191], v[190:191]
	v_pk_mul_f32 v[186:187], v[192:193], v[192:193]
	v_pk_mul_f32 v[196:197], v[42:43], v[112:113] op_sel_hi:[1,0]
	v_pk_mov_b32 v[194:195], v[188:189], v[186:187] op_sel:[1,0]
	v_mov_b32_e32 v189, v187
	v_pk_add_f32 v[186:187], v[194:195], v[188:189]
	v_pk_mul_f32 v[194:195], v[40:41], v[112:113] op_sel_hi:[1,0]
	v_pk_mul_f32 v[188:189], v[196:197], v[196:197]
	v_pk_mul_f32 v[198:199], v[194:195], v[194:195]
	v_pk_mul_f32 v[202:203], v[36:37], v[112:113] op_sel_hi:[1,0]
	v_pk_mov_b32 v[200:201], v[198:199], v[188:189] op_sel:[1,0]
	v_mov_b32_e32 v199, v189
	v_pk_mul_f32 v[224:225], v[38:39], v[112:113] op_sel_hi:[1,0]
	v_pk_add_f32 v[188:189], v[200:201], v[198:199]
	v_pk_mul_f32 v[198:199], v[224:225], v[224:225]
	v_pk_mul_f32 v[200:201], v[202:203], v[202:203]
	v_add_f32_e32 v213, v198, v199
	v_add_f32_e32 v211, v200, v201
	v_pk_mul_f32 v[198:199], v[32:33], v[112:113] op_sel_hi:[1,0]
	v_pk_mul_f32 v[200:201], v[34:35], v[112:113] op_sel_hi:[1,0]
	v_pk_add_f32 v[186:187], v[186:187], v[186:187] op_sel_hi:[0,1]
	v_pk_add_f32 v[188:189], v[188:189], v[188:189] op_sel_hi:[0,1]
	v_pk_mul_f32 v[226:227], v[200:201], v[200:201]
	v_pk_mul_f32 v[228:229], v[198:199], v[198:199]
	v_mov_b32_e32 v186, v226
	v_mov_b32_e32 v210, v228
	v_mov_b32_e32 v212, v229
	v_mov_b32_e32 v188, v227
	v_pk_add_f32 v[210:211], v[210:211], v[212:213]
	v_pk_add_f32 v[186:187], v[186:187], v[188:189]
	s_nop 0
	v_pk_add_f32 v[186:187], v[210:211], v[186:187]
	s_nop 0
	v_add_f32_e32 v112, v186, v187
	ds_bpermute_b32 v186, v209, v112
	s_waitcnt lgkmcnt(0)
	v_add_f32_e32 v112, v112, v186
	ds_bpermute_b32 v186, v222, v112
	s_waitcnt lgkmcnt(0)
	v_add_f32_e32 v112, v112, v186
	v_lshlrev_b64 v[186:187], 7, v[114:115]
	v_lshl_add_u64 v[226:227], v[170:171], 0, v[186:187]
	v_lshl_add_u64 v[228:229], v[172:173], 0, v[186:187]
	flat_load_dwordx4 v[186:189], v[226:227]
	flat_load_dwordx4 v[210:213], v[228:229]
	flat_load_dwordx4 v[246:249], v[226:227] offset:16
	flat_load_dwordx4 v[250:253], v[228:229] offset:16
	v_fmamk_f32 v112, v112, 0x3c800000, v231
	v_rsq_f32_e32 v112, v112
	s_nop 0
	v_pk_mul_f32 v[190:191], v[190:191], v[112:113] op_sel_hi:[1,0]
	v_pk_mul_f32 v[192:193], v[192:193], v[112:113] op_sel_hi:[1,0]
	v_pk_mul_f32 v[232:233], v[144:145], v[190:191]
	v_pk_mul_f32 v[190:191], v[202:203], v[112:113] op_sel_hi:[1,0]
	v_pk_mul_f32 v[242:243], v[146:147], v[192:193]
	v_pk_mul_f32 v[192:193], v[224:225], v[112:113] op_sel_hi:[1,0]
	v_pk_mul_f32 v[224:225], v[140:141], v[190:191]
	v_pk_mul_f32 v[202:203], v[142:143], v[192:193]
	v_pk_mul_f32 v[196:197], v[196:197], v[112:113] op_sel_hi:[1,0]
	v_pk_mul_f32 v[194:195], v[194:195], v[112:113] op_sel_hi:[1,0]
	s_waitcnt vmcnt(0) lgkmcnt(0)
	v_pk_mul_f32 v[192:193], v[210:211], v[224:225]
	v_pk_mul_f32 v[190:191], v[212:213], v[202:203]
	v_pk_fma_f32 v[192:193], v[186:187], v[232:233], v[192:193] neg_lo:[0,0,1] neg_hi:[0,0,1]
	v_pk_mul_f32 v[224:225], v[186:187], v[224:225]
	v_pk_mul_f32 v[186:187], v[188:189], v[202:203]
	v_pk_fma_f32 v[190:191], v[188:189], v[242:243], v[190:191] neg_lo:[0,0,1] neg_hi:[0,0,1]
	v_pk_fma_f32 v[186:187], v[212:213], v[242:243], v[186:187]
	v_pk_fma_f32 v[188:189], v[210:211], v[232:233], v[224:225]
	v_mov_b64_e32 v[210:211], v[246:247]
	v_mov_b64_e32 v[212:213], v[248:249]
	s_nop 0
	v_mov_b64_e32 v[224:225], v[250:251]
	v_mov_b64_e32 v[226:227], v[252:253]
	v_pk_mul_f32 v[202:203], v[136:137], v[194:195]
	v_pk_mul_f32 v[194:195], v[138:139], v[196:197]
	v_pk_mul_f32 v[196:197], v[198:199], v[112:113] op_sel_hi:[1,0]
	v_pk_mul_f32 v[198:199], v[200:201], v[112:113] op_sel_hi:[1,0]
	v_pk_mul_f32 v[196:197], v[132:133], v[196:197]
	v_pk_mul_f32 v[228:229], v[134:135], v[198:199]
	s_waitcnt vmcnt(0) lgkmcnt(0)
	v_pk_mul_f32 v[200:201], v[224:225], v[196:197]
	v_pk_mul_f32 v[198:199], v[226:227], v[228:229]
	v_pk_fma_f32 v[200:201], v[210:211], v[202:203], v[200:201] neg_lo:[0,0,1] neg_hi:[0,0,1]
	v_pk_mul_f32 v[196:197], v[210:211], v[196:197]
	v_pk_mul_f32 v[210:211], v[212:213], v[228:229]
	v_pk_fma_f32 v[198:199], v[212:213], v[194:195], v[198:199] neg_lo:[0,0,1] neg_hi:[0,0,1]
	v_pk_fma_f32 v[194:195], v[226:227], v[194:195], v[210:211]
	v_pk_fma_f32 v[196:197], v[224:225], v[202:203], v[196:197]
	s_cbranch_vccnz .LBB0_429
	v_pk_add_f32 v[162:163], v[162:163], v[190:191]
	v_pk_add_f32 v[160:161], v[160:161], v[192:193]
	v_pk_add_f32 v[158:159], v[158:159], v[198:199]
	v_pk_add_f32 v[156:157], v[156:157], v[200:201]
	v_pk_add_f32 v[154:155], v[154:155], v[186:187]
	v_pk_add_f32 v[152:153], v[152:153], v[188:189]
	v_pk_add_f32 v[150:151], v[150:151], v[194:195]
	v_pk_add_f32 v[148:149], v[148:149], v[196:197]
; __device__ __forceinline__ u32x4 pack8(const f32x4 a, const f32x4 b) { u32x4 w; w.x = cvt_pk_bf16(a[0], a[1]); w.y = cvt_pk_bf16(a[2], a[3]); w.z = cvt_pk_bf16(b[0], b[1]); w.w = cvt_pk_bf16(b[2], b[3]); return w; }
;     __device__ __forceinline__ void operator()(const f32x4 (&acc)[2][2][4][2], const Unit& u, int wr, int wc, int fr, int fq) const {
;     ...
;                 for (int m = 0; m < 4; ++m) { if (m == 0) asm volatile("" ::: "memory"); const int row = row0 + ai * HALF + m * 16; const float rs = rstd_of(ssq, row);
;                     f32x4 v[2][2]; float ss = 0.f;
; #pragma unroll
;                     for (int bj = 0; bj < 2; ++bj)
; #pragma unroll
;                         for (int n = 0; n < 2; ++n) { v[bj][n] = acc[ai][bj][m][n] * rs; const f32x4 q = v[bj][n] * v[bj][n]; ss += (q[0] + q[1]) + (q[2] + q[3]); }
;                     ss += __shfl_xor(ss, 16); ss += __shfl_xor(ss, 32);
;                     const float rn = __builtin_amdgcn_rsqf(ss * (1.0f / 64.0f) + 1e-6f);
;                     f32x4 o[2][2];
; #pragma unroll
;                     for (int n = 0; n < 2; ++n) { const f32x4 c = *(const f32x4*)(cosT + (size_t)row * 32 + 8 * fq + 4 * n), s = *(const f32x4*)(sinT + (size_t)row * 32 + 8 * fq + 4 * n);
;                         const f32x4 y1 = v[0][n] * rn * gv[0][n], y2 = v[1][n] * rn * gv[1][n];
;                         o[0][n] = y1 * c - y2 * s; o[1][n] = y2 * c + y1 * s; }
;                     if (dok) {
; #pragma unroll
;                         for (int bj = 0; bj < 2; ++bj)
; #pragma unroll
;                             for (int n = 0; n < 2; ++n) cs[bj][n] = cs[bj][n] + o[bj][n]; }
; #pragma unroll
;                     for (int bj = 0; bj < 2; ++bj) *(u32x4*)(ob + (size_t)row * 2816 + 32 * bj) = pack8(o[bj][0] * osc, o[bj][1] * osc); }
.LBB0_429:
	v_mad_i64_i32 v[202:203], s[12:13], v114, s92, v[180:181]
	v_mov_b32_e32 v114, v184
	v_mov_b32_e32 v115, v184
	v_pk_mul_f32 v[210:211], v[114:115], v[190:191]
	v_pk_mul_f32 v[190:191], v[184:185], v[192:193]
	v_pk_mul_f32 v[198:199], v[114:115], v[198:199]
	v_pk_mul_f32 v[192:193], v[184:185], v[200:201]
	v_cvt_pk_bf16_f32 v190, v190, v191
	v_cvt_pk_bf16_f32 v191, v210, v211
	v_cvt_pk_bf16_f32 v192, v192, v193
	v_cvt_pk_bf16_f32 v193, v198, v199
	flat_store_dwordx4 v[202:203], v[190:193]
	s_and_b64 vcc, exec, s[10:11]
	s_nop 0
	v_pk_mul_f32 v[190:191], v[114:115], v[186:187]
	v_pk_mul_f32 v[186:187], v[184:185], v[188:189]
	v_pk_mul_f32 v[192:193], v[114:115], v[194:195]
	v_pk_mul_f32 v[188:189], v[184:185], v[196:197]
	v_cvt_pk_bf16_f32 v186, v186, v187
	v_cvt_pk_bf16_f32 v187, v190, v191
	v_cvt_pk_bf16_f32 v188, v188, v189
	v_cvt_pk_bf16_f32 v189, v192, v193
	flat_store_dwordx4 v[202:203], v[186:189] offset:64
	s_nop 1
	v_add_u32_e32 v186, 0xa0, v182
	v_ashrrev_i32_e32 v187, 31, v186
	v_lshl_add_u64 v[188:189], v[186:187], 4, s[18:19]
	flat_load_dwordx4 v[188:191], v[188:189]
	s_waitcnt vmcnt(0) lgkmcnt(0)
	v_mov_b32_e32 v192, v189
	v_mov_b32_e32 v193, v190
	v_mov_b32_e32 v189, v191
	v_pk_add_f32 v[188:189], v[192:193], v[188:189]
	s_nop 0
	v_add_f32_e32 v112, v188, v189
	v_fmamk_f32 v112, v112, 0x3a800000, v231
	v_rsq_f32_e32 v112, v112
	s_nop 0
	v_pk_mul_f32 v[192:193], v[28:29], v[112:113] op_sel_hi:[1,0]
	v_pk_mul_f32 v[194:195], v[30:31], v[112:113] op_sel_hi:[1,0]
	v_pk_mul_f32 v[190:191], v[192:193], v[192:193]
	v_pk_mul_f32 v[188:189], v[194:195], v[194:195]
	v_pk_mul_f32 v[198:199], v[26:27], v[112:113] op_sel_hi:[1,0]
	v_pk_mov_b32 v[196:197], v[190:191], v[188:189] op_sel:[1,0]
	v_mov_b32_e32 v191, v189
	v_pk_add_f32 v[188:189], v[196:197], v[190:191]
	v_pk_mul_f32 v[196:197], v[24:25], v[112:113] op_sel_hi:[1,0]
	v_pk_mul_f32 v[190:191], v[198:199], v[198:199]
	v_pk_mul_f32 v[200:201], v[196:197], v[196:197]
	v_pk_mul_f32 v[224:225], v[20:21], v[112:113] op_sel_hi:[1,0]
	v_pk_mov_b32 v[202:203], v[200:201], v[190:191] op_sel:[1,0]
	v_mov_b32_e32 v201, v191
	v_pk_mul_f32 v[226:227], v[22:23], v[112:113] op_sel_hi:[1,0]
	v_pk_add_f32 v[190:191], v[202:203], v[200:201]
	v_pk_mul_f32 v[200:201], v[226:227], v[226:227]
	v_pk_mul_f32 v[202:203], v[224:225], v[224:225]
	v_add_f32_e32 v213, v200, v201
	v_add_f32_e32 v211, v202, v203
	v_pk_mul_f32 v[200:201], v[16:17], v[112:113] op_sel_hi:[1,0]
	v_pk_mul_f32 v[202:203], v[18:19], v[112:113] op_sel_hi:[1,0]
	v_pk_add_f32 v[188:189], v[188:189], v[188:189] op_sel_hi:[0,1]
	v_pk_add_f32 v[190:191], v[190:191], v[190:191] op_sel_hi:[0,1]
	v_pk_mul_f32 v[228:229], v[202:203], v[202:203]
	v_pk_mul_f32 v[232:233], v[200:201], v[200:201]
	v_mov_b32_e32 v188, v228
	v_mov_b32_e32 v210, v232
	v_mov_b32_e32 v212, v233
	v_mov_b32_e32 v190, v229
	v_pk_add_f32 v[210:211], v[210:211], v[212:213]
	v_pk_add_f32 v[188:189], v[188:189], v[190:191]
	s_nop 0
	v_pk_add_f32 v[188:189], v[210:211], v[188:189]
	s_nop 0
	v_add_f32_e32 v112, v188, v189
	ds_bpermute_b32 v188, v209, v112
	s_waitcnt lgkmcnt(0)
	v_add_f32_e32 v112, v112, v188
	ds_bpermute_b32 v188, v222, v112
	s_waitcnt lgkmcnt(0)
	v_add_f32_e32 v112, v112, v188
	v_lshlrev_b64 v[188:189], 7, v[186:187]
	v_lshl_add_u64 v[228:229], v[170:171], 0, v[188:189]
	v_lshl_add_u64 v[232:233], v[172:173], 0, v[188:189]
	flat_load_dwordx4 v[188:191], v[228:229]
	flat_load_dwordx4 v[210:213], v[232:233]
	flat_load_dwordx4 v[246:249], v[228:229] offset:16
	flat_load_dwordx4 v[250:253], v[232:233] offset:16
	v_fmamk_f32 v112, v112, 0x3c800000, v231
	v_rsq_f32_e32 v112, v112
	s_nop 0
	v_pk_mul_f32 v[192:193], v[192:193], v[112:113] op_sel_hi:[1,0]
	v_pk_mul_f32 v[194:195], v[194:195], v[112:113] op_sel_hi:[1,0]
	v_pk_mul_f32 v[242:243], v[144:145], v[192:193]
	v_pk_mul_f32 v[192:193], v[224:225], v[112:113] op_sel_hi:[1,0]
	v_pk_mul_f32 v[244:245], v[146:147], v[194:195]
	v_pk_mul_f32 v[194:195], v[226:227], v[112:113] op_sel_hi:[1,0]
	v_pk_mul_f32 v[226:227], v[140:141], v[192:193]
	v_pk_mul_f32 v[224:225], v[142:143], v[194:195]
	v_pk_mul_f32 v[198:199], v[198:199], v[112:113] op_sel_hi:[1,0]
	v_pk_mul_f32 v[196:197], v[196:197], v[112:113] op_sel_hi:[1,0]
	s_waitcnt vmcnt(0) lgkmcnt(0)
	v_pk_mul_f32 v[194:195], v[210:211], v[226:227]
	v_pk_mul_f32 v[192:193], v[212:213], v[224:225]
	v_pk_fma_f32 v[194:195], v[188:189], v[242:243], v[194:195] neg_lo:[0,0,1] neg_hi:[0,0,1]
	v_pk_mul_f32 v[226:227], v[188:189], v[226:227]
	v_pk_mul_f32 v[188:189], v[190:191], v[224:225]
	v_pk_fma_f32 v[192:193], v[190:191], v[244:245], v[192:193] neg_lo:[0,0,1] neg_hi:[0,0,1]
	v_pk_fma_f32 v[188:189], v[212:213], v[244:245], v[188:189]
	v_pk_fma_f32 v[190:191], v[210:211], v[242:243], v[226:227]
	v_mov_b64_e32 v[210:211], v[246:247]
	v_mov_b64_e32 v[212:213], v[248:249]
	v_mov_b64_e32 v[224:225], v[250:251]
	v_mov_b64_e32 v[226:227], v[252:253]
	v_pk_mul_f32 v[228:229], v[136:137], v[196:197]
	v_pk_mul_f32 v[196:197], v[138:139], v[198:199]
	v_pk_mul_f32 v[198:199], v[200:201], v[112:113] op_sel_hi:[1,0]
	v_pk_mul_f32 v[200:201], v[202:203], v[112:113] op_sel_hi:[1,0]
	v_pk_mul_f32 v[198:199], v[132:133], v[198:199]
	v_pk_mul_f32 v[232:233], v[134:135], v[200:201]
	s_waitcnt vmcnt(0) lgkmcnt(0)
	v_pk_mul_f32 v[202:203], v[224:225], v[198:199]
	v_pk_mul_f32 v[200:201], v[226:227], v[232:233]
	v_pk_fma_f32 v[202:203], v[210:211], v[228:229], v[202:203] neg_lo:[0,0,1] neg_hi:[0,0,1]
	v_pk_mul_f32 v[198:199], v[210:211], v[198:199]
	v_pk_mul_f32 v[210:211], v[212:213], v[232:233]
	v_pk_fma_f32 v[200:201], v[212:213], v[196:197], v[200:201] neg_lo:[0,0,1] neg_hi:[0,0,1]
	v_pk_fma_f32 v[196:197], v[226:227], v[196:197], v[210:211]
	v_pk_fma_f32 v[198:199], v[224:225], v[228:229], v[198:199]
	s_cbranch_vccnz .LBB0_431
	v_pk_add_f32 v[162:163], v[162:163], v[192:193]
	v_pk_add_f32 v[160:161], v[160:161], v[194:195]
	v_pk_add_f32 v[158:159], v[158:159], v[200:201]
	v_pk_add_f32 v[156:157], v[156:157], v[202:203]
	v_pk_add_f32 v[154:155], v[154:155], v[188:189]
	v_pk_add_f32 v[152:153], v[152:153], v[190:191]
	v_pk_add_f32 v[150:151], v[150:151], v[196:197]
	v_pk_add_f32 v[148:149], v[148:149], v[198:199]
; __device__ __forceinline__ u32x4 pack8(const f32x4 a, const f32x4 b) { u32x4 w; w.x = cvt_pk_bf16(a[0], a[1]); w.y = cvt_pk_bf16(a[2], a[3]); w.z = cvt_pk_bf16(b[0], b[1]); w.w = cvt_pk_bf16(b[2], b[3]); return w; }
;     __device__ __forceinline__ void operator()(const f32x4 (&acc)[2][2][4][2], const Unit& u, int wr, int wc, int fr, int fq) const {
;     ...
;                 for (int m = 0; m < 4; ++m) { if (m == 0) asm volatile("" ::: "memory"); const int row = row0 + ai * HALF + m * 16; const float rs = rstd_of(ssq, row);
;                     f32x4 v[2][2]; float ss = 0.f;
; #pragma unroll
;                     for (int bj = 0; bj < 2; ++bj)
; #pragma unroll
;                         for (int n = 0; n < 2; ++n) { v[bj][n] = acc[ai][bj][m][n] * rs; const f32x4 q = v[bj][n] * v[bj][n]; ss += (q[0] + q[1]) + (q[2] + q[3]); }
;                     ss += __shfl_xor(ss, 16); ss += __shfl_xor(ss, 32);
;                     const float rn = __builtin_amdgcn_rsqf(ss * (1.0f / 64.0f) + 1e-6f);
;                     f32x4 o[2][2];
; #pragma unroll
;                     for (int n = 0; n < 2; ++n) { const f32x4 c = *(const f32x4*)(cosT + (size_t)row * 32 + 8 * fq + 4 * n), s = *(const f32x4*)(sinT + (size_t)row * 32 + 8 * fq + 4 * n);
;                         const f32x4 y1 = v[0][n] * rn * gv[0][n], y2 = v[1][n] * rn * gv[1][n];
;                         o[0][n] = y1 * c - y2 * s; o[1][n] = y2 * c + y1 * s; }
;                     if (dok) {
; #pragma unroll
;                         for (int bj = 0; bj < 2; ++bj)
; #pragma unroll
;                             for (int n = 0; n < 2; ++n) cs[bj][n] = cs[bj][n] + o[bj][n]; }
; #pragma unroll
;                     for (int bj = 0; bj < 2; ++bj) *(u32x4*)(ob + (size_t)row * 2816 + 32 * bj) = pack8(o[bj][0] * osc, o[bj][1] * osc); }
.LBB0_431:
	v_mad_i64_i32 v[210:211], s[12:13], v186, s92, v[180:181]
	v_pk_mul_f32 v[186:187], v[114:115], v[192:193]
	v_pk_mul_f32 v[192:193], v[184:185], v[194:195]
	v_pk_mul_f32 v[200:201], v[114:115], v[200:201]
	v_cvt_pk_bf16_f32 v192, v192, v193
	v_cvt_pk_bf16_f32 v193, v186, v187
	v_pk_mul_f32 v[188:189], v[114:115], v[188:189]
	v_pk_mul_f32 v[186:187], v[184:185], v[190:191]
	v_pk_mul_f32 v[114:115], v[114:115], v[196:197]
	v_pk_mul_f32 v[194:195], v[184:185], v[202:203]
	v_pk_mul_f32 v[190:191], v[184:185], v[198:199]
	v_cvt_pk_bf16_f32 v186, v186, v187
	v_cvt_pk_bf16_f32 v187, v188, v189
	v_cvt_pk_bf16_f32 v189, v114, v115
	v_add_u32_e32 v114, 0xb0, v182
	v_cvt_pk_bf16_f32 v194, v194, v195
	v_cvt_pk_bf16_f32 v195, v200, v201
	v_cvt_pk_bf16_f32 v188, v190, v191
	v_ashrrev_i32_e32 v115, 31, v114
	flat_store_dwordx4 v[210:211], v[192:195]
	flat_store_dwordx4 v[210:211], v[186:189] offset:64
	s_and_b64 vcc, exec, s[10:11]
	s_nop 0
	v_lshl_add_u64 v[186:187], v[114:115], 4, s[18:19]
	flat_load_dwordx4 v[186:189], v[186:187]
	s_waitcnt vmcnt(0) lgkmcnt(0)
	v_mov_b32_e32 v190, v187
	v_mov_b32_e32 v191, v188
	v_mov_b32_e32 v187, v189
	v_pk_add_f32 v[186:187], v[190:191], v[186:187]
	s_nop 0
	v_add_f32_e32 v112, v186, v187
	v_fmamk_f32 v112, v112, 0x3a800000, v231
	v_rsq_f32_e32 v112, v112
	s_nop 0
	v_pk_mul_f32 v[202:203], v[12:13], v[112:113] op_sel_hi:[1,0]
	v_pk_mul_f32 v[210:211], v[14:15], v[112:113] op_sel_hi:[1,0]
	v_pk_mul_f32 v[188:189], v[202:203], v[202:203]
	v_pk_mul_f32 v[186:187], v[210:211], v[210:211]
	v_pk_mul_f32 v[212:213], v[4:5], v[112:113] op_sel_hi:[1,0]
	v_pk_mov_b32 v[190:191], v[188:189], v[186:187] op_sel:[1,0]
	v_mov_b32_e32 v189, v187
	v_pk_add_f32 v[186:187], v[190:191], v[188:189]
	v_pk_mul_f32 v[188:189], v[10:11], v[112:113] op_sel_hi:[1,0]
	v_pk_add_f32 v[194:195], v[186:187], v[186:187] op_sel_hi:[0,1]
	v_pk_mul_f32 v[186:187], v[8:9], v[112:113] op_sel_hi:[1,0]
	v_pk_mul_f32 v[190:191], v[188:189], v[188:189]
	v_pk_mul_f32 v[192:193], v[186:187], v[186:187]
	v_pk_mul_f32 v[224:225], v[6:7], v[112:113] op_sel_hi:[1,0]
	v_pk_mov_b32 v[196:197], v[192:193], v[190:191] op_sel:[1,0]
	v_mov_b32_e32 v193, v191
	v_pk_add_f32 v[190:191], v[196:197], v[192:193]
	v_pk_mul_f32 v[192:193], v[212:213], v[212:213]
	v_pk_add_f32 v[196:197], v[190:191], v[190:191] op_sel_hi:[0,1]
	v_pk_mul_f32 v[190:191], v[224:225], v[224:225]
	v_add_f32_e32 v199, v192, v193
	v_add_f32_e32 v201, v190, v191
	v_pk_mul_f32 v[190:191], v[0:1], v[112:113] op_sel_hi:[1,0]
	v_pk_mul_f32 v[192:193], v[2:3], v[112:113] op_sel_hi:[1,0]
	v_pk_mul_f32 v[228:229], v[190:191], v[190:191]
	v_pk_mul_f32 v[226:227], v[192:193], v[192:193]
	v_mov_b32_e32 v198, v228
	v_mov_b32_e32 v200, v229
	v_mov_b32_e32 v194, v226
	v_mov_b32_e32 v196, v227
	v_pk_add_f32 v[198:199], v[198:199], v[200:201]
	v_pk_add_f32 v[194:195], v[194:195], v[196:197]
	s_nop 0
	v_pk_add_f32 v[194:195], v[198:199], v[194:195]
	s_nop 0
	v_add_f32_e32 v112, v194, v195
	ds_bpermute_b32 v194, v209, v112
	s_waitcnt lgkmcnt(0)
	v_add_f32_e32 v112, v112, v194
	ds_bpermute_b32 v194, v222, v112
	s_waitcnt lgkmcnt(0)
	v_add_f32_e32 v112, v112, v194
	v_lshlrev_b64 v[194:195], 7, v[114:115]
	v_lshl_add_u64 v[222:223], v[170:171], 0, v[194:195]
	v_lshl_add_u64 v[226:227], v[172:173], 0, v[194:195]
	flat_load_dwordx4 v[194:197], v[222:223]
	flat_load_dwordx4 v[198:201], v[226:227]
	flat_load_dwordx4 v[246:249], v[222:223] offset:16
	flat_load_dwordx4 v[250:253], v[226:227] offset:16
	v_fmamk_f32 v112, v112, 0x3c800000, v231
	v_rsq_f32_e32 v112, v112
	s_nop 0
	v_pk_mul_f32 v[202:203], v[202:203], v[112:113] op_sel_hi:[1,0]
	v_pk_mul_f32 v[210:211], v[210:211], v[112:113] op_sel_hi:[1,0]
	v_pk_mul_f32 v[202:203], v[144:145], v[202:203]
	v_pk_mul_f32 v[144:145], v[212:213], v[112:113] op_sel_hi:[1,0]
	v_pk_mul_f32 v[210:211], v[146:147], v[210:211]
	v_pk_mul_f32 v[146:147], v[224:225], v[112:113] op_sel_hi:[1,0]
	v_pk_mul_f32 v[140:141], v[140:141], v[144:145]
	v_pk_mul_f32 v[142:143], v[142:143], v[146:147]
	v_pk_mul_f32 v[188:189], v[188:189], v[112:113] op_sel_hi:[1,0]
	v_pk_mul_f32 v[186:187], v[186:187], v[112:113] op_sel_hi:[1,0]
	v_pk_mul_f32 v[188:189], v[138:139], v[188:189]
	v_pk_mul_f32 v[186:187], v[136:137], v[186:187]
	v_pk_mul_f32 v[136:137], v[190:191], v[112:113] op_sel_hi:[1,0]
	v_pk_mul_f32 v[138:139], v[192:193], v[112:113] op_sel_hi:[1,0]
	v_pk_mul_f32 v[132:133], v[132:133], v[136:137]
	v_pk_mul_f32 v[134:135], v[134:135], v[138:139]
	s_waitcnt vmcnt(0) lgkmcnt(0)
	v_pk_mul_f32 v[146:147], v[198:199], v[140:141]
	v_pk_mul_f32 v[144:145], v[200:201], v[142:143]
	v_pk_fma_f32 v[146:147], v[194:195], v[202:203], v[146:147] neg_lo:[0,0,1] neg_hi:[0,0,1]
	v_pk_mul_f32 v[194:195], v[194:195], v[140:141]
	v_pk_mul_f32 v[140:141], v[196:197], v[142:143]
	v_pk_fma_f32 v[144:145], v[196:197], v[210:211], v[144:145] neg_lo:[0,0,1] neg_hi:[0,0,1]
	v_pk_fma_f32 v[140:141], v[200:201], v[210:211], v[140:141]
	v_pk_fma_f32 v[142:143], v[198:199], v[202:203], v[194:195]
	v_mov_b64_e32 v[194:195], v[246:247]
	v_mov_b64_e32 v[196:197], v[248:249]
	v_mov_b64_e32 v[198:199], v[250:251]
	v_mov_b64_e32 v[200:201], v[252:253]
	s_waitcnt vmcnt(0) lgkmcnt(0)
	v_pk_mul_f32 v[190:191], v[194:195], v[132:133]
	v_pk_mul_f32 v[138:139], v[198:199], v[132:133]
	v_pk_mul_f32 v[136:137], v[200:201], v[134:135]
	v_pk_mul_f32 v[132:133], v[196:197], v[134:135]
	v_pk_fma_f32 v[136:137], v[196:197], v[188:189], v[136:137] neg_lo:[0,0,1] neg_hi:[0,0,1]
	v_pk_fma_f32 v[138:139], v[194:195], v[186:187], v[138:139] neg_lo:[0,0,1] neg_hi:[0,0,1]
	v_pk_fma_f32 v[132:133], v[200:201], v[188:189], v[132:133]
	v_pk_fma_f32 v[134:135], v[198:199], v[186:187], v[190:191]
	s_cbranch_vccnz .LBB0_433
	v_pk_add_f32 v[162:163], v[162:163], v[144:145]
	v_pk_add_f32 v[160:161], v[160:161], v[146:147]
	v_pk_add_f32 v[158:159], v[158:159], v[136:137]
	v_pk_add_f32 v[156:157], v[156:157], v[138:139]
	v_pk_add_f32 v[154:155], v[154:155], v[140:141]
	v_pk_add_f32 v[152:153], v[152:153], v[142:143]
	v_pk_add_f32 v[150:151], v[150:151], v[132:133]
	v_pk_add_f32 v[148:149], v[148:149], v[134:135]
